# select stage 1 inner loop hand-pipelined (LDS reads / MFMA / relu-sum overlap), counted waits for k_idx prefetch; scan chains remapped for XCD L2 sharing
# speedup vs baseline: 1.0039x; 1.0039x over previous
; __device__ __forceinline__ void dsa_select_item(CParams& p, LAS unsigned char* lds, int b, int qblk, int tid_in, int wave) {
;     ...
;         __syncthreads();
;         const int r = lane & 31, hk = lane >> 5;
;         const int nk32 = qblk + 1;
;         const h16* kp0 = proj + (size_t)(tb0 + r) * OD_N + 2816 + 8 * hk;
;         h16x8 bf[4], bn[4];
;         if (wave < nk32) {
; #pragma unroll
;             for (int s = 0; s < 4; ++s) bf[s] = *(const h16x8*)(kp0 + (size_t)wave * 32 * OD_N + 16 * s);
;         }
;         for (int kt = wave; kt < nk32; kt += 8) {
;             const int ktn = kt + 8 < nk32 ? kt + 8 : kt;
; #pragma unroll
;             for (int s = 0; s < 4; ++s) bn[s] = *(const h16x8*)(kp0 + (size_t)ktn * 32 * OD_N + 16 * s);
;             const int kp = kt * 32 + r;
.LBB0_402:
	s_or_b64 exec, exec, s[4:5]
	s_lshl_b32 s85, s83, 1
	v_and_b32_e32 v58, 63, v2
	v_cmp_ge_i32_e32 vcc, s85, v182
	s_waitcnt lgkmcnt(0)
	s_barrier
	s_and_saveexec_b64 s[4:5], vcc
	s_cbranch_execz .LBB0_407
	v_and_b32_e32 v59, 31, v2
	v_or_b32_e32 v0, s58, v59
	v_lshrrev_b32_e32 v6, 5, v58
	v_mul_u32_u24_e32 v0, 0x1800, v0
	v_lshl_add_u64 v[4:5], s[14:15], 0, v[0:1]
	v_lshlrev_b32_e32 v0, 4, v6
	v_lshl_add_u64 v[4:5], v[4:5], 0, v[0:1]
	s_mov_b64 s[6:7], 0x1600
	v_lshl_add_u64 v[50:51], v[4:5], 0, s[6:7]
	v_lshl_add_u64 v[4:5], v[50:51], 0, v[134:135]
	global_load_dwordx4 v[18:21], v[4:5], off
	global_load_dwordx4 v[22:25], v[4:5], off offset:32
	global_load_dwordx4 v[26:29], v[4:5], off offset:64
	global_load_dwordx4 v[30:33], v[4:5], off offset:96
	v_lshlrev_b32_e32 v2, 10, v2
	v_and_b32_e32 v2, 0x8000, v2
	v_mov_b32_e32 v3, v1
	v_lshl_add_u64 v[52:53], s[28:29], 0, v[2:3]
	v_mul_u32_u24_e32 v2, 0x90, v59
	s_add_i32 s12, 0, 0xa000
	v_add_u32_e32 v54, v190, v59
	v_lshl_add_u32 v60, v6, 1, s84
	v_lshl_add_u32 v61, v6, 6, 0
	v_add3_u32 v0, v2, v0, s12
	s_mov_b64 s[12:13], 0
	v_mov_b32_e32 v62, v182
	s_waitcnt vmcnt(0)

; #define LAS __attribute__((address_space(3)))
; __device__ __forceinline__ f32x16 mma32(const h16x8 a, const h16x8 b, const f32x16 c) { return __builtin_amdgcn_mfma_f32_32x32x16_f16(a, b, c, 0, 0, 0); }
; __device__ __forceinline__ void dsa_select_item(CParams& p, LAS unsigned char* lds, int b, int qblk, int tid_in, int wave) {
;     ...
; #pragma unroll 1
;             for (int a = 0; a < 8; ++a) {
;                 f32x16 acc;
; #pragma unroll
;                 for (int i = 0; i < 16; ++i) acc[i] = 0.f;
; #pragma unroll
;                 for (int s = 0; s < 4; ++s) acc = mma32(*(const LAS h16x8*)(Aq + (32 * a + r) * 72 + 16 * s + 8 * hk), bf[s], acc);
; #pragma unroll
;                 for (int qq = 0; qq < 2; ++qq) { const int qi = 4 * a + 2 * hk + qq;
;                     const f32x4 w0 = *(const LAS f32x4*)(Wq + qi * 8), w1 = *(const LAS f32x4*)(Wq + qi * 8 + 4);
;                     float sv = 0.f;
; #pragma unroll
;                     for (int e = 0; e < 4; ++e) { sv += w0[e] * fmaxf(acc[8 * qq + e], 0.f); sv += w1[e] * fmaxf(acc[8 * qq + 4 + e], 0.f); }
;                     const int qpq = qblk * 32 + qi;
;                     scw[(size_t)qi * 4096 + kp] = kp <= qpq ? sv : -INFINITY; }
.LBB0_405:
	v_lshlrev_b32_e32 v144, 9, v61
	v_lshl_add_u32 v144, v55, 2, v144
	v_mov_b32_e32 v145, v60
	v_add_u32_e32 v146, 1, v60
	s_mov_b64 s[36:37], s[18:19]
	v_mov_b32_e32 v147, v0
	ds_read_b128 v[66:69], v147 offset:0
	ds_read_b128 v[70:73], v147 offset:32
	ds_read_b128 v[74:77], v147 offset:64
	ds_read_b128 v[78:81], v147 offset:96
	v_add_u32_e32 v148, 0x13000, v61
	ds_read_b128 v[114:117], v148 offset:0
	ds_read_b128 v[118:121], v148 offset:16
	ds_read_b128 v[122:125], v148 offset:32
	ds_read_b128 v[126:129], v148 offset:48
	v_add_u32_e32 v147, 0x1200, v147
	ds_read_b128 v[82:85], v147 offset:0
	ds_read_b128 v[86:89], v147 offset:32
	ds_read_b128 v[90:93], v147 offset:64
	ds_read_b128 v[94:97], v147 offset:96
	v_add_u32_e32 v148, 0x80, v148
	ds_read_b128 v[228:231], v148 offset:0
	ds_read_b128 v[232:235], v148 offset:16
	ds_read_b128 v[236:239], v148 offset:32
	ds_read_b128 v[240:243], v148 offset:48
	s_waitcnt lgkmcnt(12)
	v_mfma_f32_32x32x16_f16 v[2:17], v[66:69], v[18:21], 0
	v_mfma_f32_32x32x16_f16 v[2:17], v[70:73], v[22:25], v[2:17]
	v_mfma_f32_32x32x16_f16 v[2:17], v[74:77], v[26:29], v[2:17]
	v_mfma_f32_32x32x16_f16 v[2:17], v[78:81], v[30:33], v[2:17]
	v_add_u32_e32 v147, 0x1200, v147
	ds_read_b128 v[66:69], v147 offset:0
	ds_read_b128 v[70:73], v147 offset:32
	ds_read_b128 v[74:77], v147 offset:64
	ds_read_b128 v[78:81], v147 offset:96
	s_waitcnt lgkmcnt(8)
	v_mfma_f32_32x32x16_f16 v[98:113], v[82:85], v[18:21], 0
	v_mfma_f32_32x32x16_f16 v[98:113], v[86:89], v[22:25], v[98:113]
	v_mfma_f32_32x32x16_f16 v[98:113], v[90:93], v[26:29], v[98:113]
	v_mfma_f32_32x32x16_f16 v[98:113], v[94:97], v[30:33], v[98:113]
	v_cmp_le_i32_e64 s[38:39], v55, v145
	v_cmp_le_i32_e64 s[40:41], v55, v146
	s_nop 3
	v_max_f32_e32 v152, 0, v2
	v_fma_f32 v150, v114, v152, 0
	v_max_f32_e32 v153, 0, v10
	v_fma_f32 v151, v122, v153, 0
	v_max_f32_e32 v152, 0, v6
	v_fmac_f32_e32 v150, v118, v152
	v_max_f32_e32 v153, 0, v14
	v_fmac_f32_e32 v151, v126, v153
	v_max_f32_e32 v152, 0, v3
	v_fmac_f32_e32 v150, v115, v152
	v_max_f32_e32 v153, 0, v11
	v_fmac_f32_e32 v151, v123, v153
	v_max_f32_e32 v152, 0, v7
	v_fmac_f32_e32 v150, v119, v152
	v_max_f32_e32 v153, 0, v15
	v_fmac_f32_e32 v151, v127, v153
	v_max_f32_e32 v152, 0, v4
	v_fmac_f32_e32 v150, v116, v152
	v_max_f32_e32 v153, 0, v12
	v_fmac_f32_e32 v151, v124, v153
	v_max_f32_e32 v152, 0, v8
	v_fmac_f32_e32 v150, v120, v152
	v_max_f32_e32 v153, 0, v16
	v_fmac_f32_e32 v151, v128, v153
	v_max_f32_e32 v152, 0, v5
	v_fmac_f32_e32 v150, v117, v152
	v_max_f32_e32 v153, 0, v13
	v_fmac_f32_e32 v151, v125, v153
	v_max_f32_e32 v152, 0, v9
	v_fmac_f32_e32 v150, v121, v152
	v_max_f32_e32 v153, 0, v17
	v_fmac_f32_e32 v151, v129, v153
	v_add_u32_e32 v145, 4, v145
	v_add_u32_e32 v146, 4, v146
	v_cndmask_b32_e64 v150, v225, v150, s[38:39]
	global_store_dword v144, v150, s[36:37]
	v_cndmask_b32_e64 v151, v225, v151, s[40:41]
	s_add_u32 s36, s36, 0x4000
	s_addc_u32 s37, s37, 0
	global_store_dword v144, v151, s[36:37]
	v_add_u32_e32 v148, 0x80, v148
	ds_read_b128 v[114:117], v148 offset:0
	ds_read_b128 v[118:121], v148 offset:16
	ds_read_b128 v[122:125], v148 offset:32
	ds_read_b128 v[126:129], v148 offset:48
	v_add_u32_e32 v147, 0x1200, v147
	ds_read_b128 v[82:85], v147 offset:0
	ds_read_b128 v[86:89], v147 offset:32
	ds_read_b128 v[90:93], v147 offset:64
	ds_read_b128 v[94:97], v147 offset:96
	s_waitcnt lgkmcnt(8)
	v_mfma_f32_32x32x16_f16 v[2:17], v[66:69], v[18:21], 0
	v_mfma_f32_32x32x16_f16 v[2:17], v[70:73], v[22:25], v[2:17]
	v_mfma_f32_32x32x16_f16 v[2:17], v[74:77], v[26:29], v[2:17]
	v_mfma_f32_32x32x16_f16 v[2:17], v[78:81], v[30:33], v[2:17]
	v_cmp_le_i32_e64 s[38:39], v55, v145
	v_cmp_le_i32_e64 s[40:41], v55, v146
	v_max_f32_e32 v152, 0, v98
	v_fma_f32 v150, v228, v152, 0
	v_max_f32_e32 v153, 0, v106
	v_fma_f32 v151, v236, v153, 0
	v_max_f32_e32 v152, 0, v102
	v_fmac_f32_e32 v150, v232, v152
	v_max_f32_e32 v153, 0, v110
	v_fmac_f32_e32 v151, v240, v153
	v_max_f32_e32 v152, 0, v99
	v_fmac_f32_e32 v150, v229, v152
	v_max_f32_e32 v153, 0, v107
	v_fmac_f32_e32 v151, v237, v153
	v_max_f32_e32 v152, 0, v103
	v_fmac_f32_e32 v150, v233, v152
	v_max_f32_e32 v153, 0, v111
	v_fmac_f32_e32 v151, v241, v153
	v_max_f32_e32 v152, 0, v100
	v_fmac_f32_e32 v150, v230, v152
	v_max_f32_e32 v153, 0, v108
	v_fmac_f32_e32 v151, v238, v153
	v_max_f32_e32 v152, 0, v104
	v_fmac_f32_e32 v150, v234, v152
	v_max_f32_e32 v153, 0, v112
	v_fmac_f32_e32 v151, v242, v153
	v_max_f32_e32 v152, 0, v101
	v_fmac_f32_e32 v150, v231, v152
	v_max_f32_e32 v153, 0, v109
	v_fmac_f32_e32 v151, v239, v153
	v_max_f32_e32 v152, 0, v105
	v_fmac_f32_e32 v150, v235, v152
	v_max_f32_e32 v153, 0, v113
	v_fmac_f32_e32 v151, v243, v153
	v_add_u32_e32 v145, 4, v145
	v_add_u32_e32 v146, 4, v146
	v_cndmask_b32_e64 v150, v225, v150, s[38:39]
	s_add_u32 s36, s36, 0xc000
	s_addc_u32 s37, s37, 0
	global_store_dword v144, v150, s[36:37]
	v_cndmask_b32_e64 v151, v225, v151, s[40:41]
	s_add_u32 s36, s36, 0x4000
	s_addc_u32 s37, s37, 0
	global_store_dword v144, v151, s[36:37]
	v_add_u32_e32 v148, 0x80, v148
	ds_read_b128 v[228:231], v148 offset:0
	ds_read_b128 v[232:235], v148 offset:16
	ds_read_b128 v[236:239], v148 offset:32
	ds_read_b128 v[240:243], v148 offset:48
	v_add_u32_e32 v147, 0x1200, v147
	ds_read_b128 v[66:69], v147 offset:0
	ds_read_b128 v[70:73], v147 offset:32
	ds_read_b128 v[74:77], v147 offset:64
	ds_read_b128 v[78:81], v147 offset:96
	s_waitcnt lgkmcnt(8)
; #define LAS __attribute__((address_space(3)))
; __device__ __forceinline__ f32x16 mma32(const h16x8 a, const h16x8 b, const f32x16 c) { return __builtin_amdgcn_mfma_f32_32x32x16_f16(a, b, c, 0, 0, 0); }
; __device__ __forceinline__ void dsa_select_item(CParams& p, LAS unsigned char* lds, int b, int qblk, int tid_in, int wave) {
;     ...
;             for (int a = 0; a < 8; ++a) {
;                 f32x16 acc;
; #pragma unroll
;                 for (int i = 0; i < 16; ++i) acc[i] = 0.f;
; #pragma unroll
;                 for (int s = 0; s < 4; ++s) acc = mma32(*(const LAS h16x8*)(Aq + (32 * a + r) * 72 + 16 * s + 8 * hk), bf[s], acc);
; #pragma unroll
;                 for (int qq = 0; qq < 2; ++qq) { const int qi = 4 * a + 2 * hk + qq;
;                     const f32x4 w0 = *(const LAS f32x4*)(Wq + qi * 8), w1 = *(const LAS f32x4*)(Wq + qi * 8 + 4);
;                     float sv = 0.f;
; #pragma unroll
;                     for (int e = 0; e < 4; ++e) { sv += w0[e] * fmaxf(acc[8 * qq + e], 0.f); sv += w1[e] * fmaxf(acc[8 * qq + 4 + e], 0.f); }
;                     const int qpq = qblk * 32 + qi;
;                     scw[(size_t)qi * 4096 + kp] = kp <= qpq ? sv : -INFINITY; }
	v_mfma_f32_32x32x16_f16 v[98:113], v[82:85], v[18:21], 0
	v_mfma_f32_32x32x16_f16 v[98:113], v[86:89], v[22:25], v[98:113]
	v_mfma_f32_32x32x16_f16 v[98:113], v[90:93], v[26:29], v[98:113]
	v_mfma_f32_32x32x16_f16 v[98:113], v[94:97], v[30:33], v[98:113]
	v_cmp_le_i32_e64 s[38:39], v55, v145
	v_cmp_le_i32_e64 s[40:41], v55, v146
	v_max_f32_e32 v152, 0, v2
	v_fma_f32 v150, v114, v152, 0
	v_max_f32_e32 v153, 0, v10
	v_fma_f32 v151, v122, v153, 0
	v_max_f32_e32 v152, 0, v6
	v_fmac_f32_e32 v150, v118, v152
	v_max_f32_e32 v153, 0, v14
	v_fmac_f32_e32 v151, v126, v153
	v_max_f32_e32 v152, 0, v3
	v_fmac_f32_e32 v150, v115, v152
	v_max_f32_e32 v153, 0, v11
	v_fmac_f32_e32 v151, v123, v153
	v_max_f32_e32 v152, 0, v7
	v_fmac_f32_e32 v150, v119, v152
	v_max_f32_e32 v153, 0, v15
	v_fmac_f32_e32 v151, v127, v153
	v_max_f32_e32 v152, 0, v4
	v_fmac_f32_e32 v150, v116, v152
	v_max_f32_e32 v153, 0, v12
	v_fmac_f32_e32 v151, v124, v153
	v_max_f32_e32 v152, 0, v8
	v_fmac_f32_e32 v150, v120, v152
	v_max_f32_e32 v153, 0, v16
	v_fmac_f32_e32 v151, v128, v153
	v_max_f32_e32 v152, 0, v5
	v_fmac_f32_e32 v150, v117, v152
	v_max_f32_e32 v153, 0, v13
	v_fmac_f32_e32 v151, v125, v153
	v_max_f32_e32 v152, 0, v9
	v_fmac_f32_e32 v150, v121, v152
	v_max_f32_e32 v153, 0, v17
	v_fmac_f32_e32 v151, v129, v153
	v_add_u32_e32 v145, 4, v145
	v_add_u32_e32 v146, 4, v146
	v_cndmask_b32_e64 v150, v225, v150, s[38:39]
	s_add_u32 s36, s36, 0xc000
	s_addc_u32 s37, s37, 0
	global_store_dword v144, v150, s[36:37]
	v_cndmask_b32_e64 v151, v225, v151, s[40:41]
	s_add_u32 s36, s36, 0x4000
	s_addc_u32 s37, s37, 0
	global_store_dword v144, v151, s[36:37]
	v_add_u32_e32 v148, 0x80, v148
	ds_read_b128 v[114:117], v148 offset:0
	ds_read_b128 v[118:121], v148 offset:16
	ds_read_b128 v[122:125], v148 offset:32
	ds_read_b128 v[126:129], v148 offset:48
	v_add_u32_e32 v147, 0x1200, v147
	ds_read_b128 v[82:85], v147 offset:0
	ds_read_b128 v[86:89], v147 offset:32
	ds_read_b128 v[90:93], v147 offset:64
	ds_read_b128 v[94:97], v147 offset:96
	s_waitcnt lgkmcnt(8)
	v_mfma_f32_32x32x16_f16 v[2:17], v[66:69], v[18:21], 0
	v_mfma_f32_32x32x16_f16 v[2:17], v[70:73], v[22:25], v[2:17]
	v_mfma_f32_32x32x16_f16 v[2:17], v[74:77], v[26:29], v[2:17]
	v_mfma_f32_32x32x16_f16 v[2:17], v[78:81], v[30:33], v[2:17]
	v_cmp_le_i32_e64 s[38:39], v55, v145
	v_cmp_le_i32_e64 s[40:41], v55, v146
	v_max_f32_e32 v152, 0, v98
	v_fma_f32 v150, v228, v152, 0
	v_max_f32_e32 v153, 0, v106
	v_fma_f32 v151, v236, v153, 0
	v_max_f32_e32 v152, 0, v102
	v_fmac_f32_e32 v150, v232, v152
	v_max_f32_e32 v153, 0, v110
	v_fmac_f32_e32 v151, v240, v153
	v_max_f32_e32 v152, 0, v99
	v_fmac_f32_e32 v150, v229, v152
	v_max_f32_e32 v153, 0, v107
	v_fmac_f32_e32 v151, v237, v153
	v_max_f32_e32 v152, 0, v103
	v_fmac_f32_e32 v150, v233, v152
	v_max_f32_e32 v153, 0, v111
	v_fmac_f32_e32 v151, v241, v153
	v_max_f32_e32 v152, 0, v100
	v_fmac_f32_e32 v150, v230, v152
	v_max_f32_e32 v153, 0, v108
	v_fmac_f32_e32 v151, v238, v153
	v_max_f32_e32 v152, 0, v104
	v_fmac_f32_e32 v150, v234, v152
	v_max_f32_e32 v153, 0, v112
	v_fmac_f32_e32 v151, v242, v153
	v_max_f32_e32 v152, 0, v101
	v_fmac_f32_e32 v150, v231, v152
	v_max_f32_e32 v153, 0, v109
	v_fmac_f32_e32 v151, v239, v153
	v_max_f32_e32 v152, 0, v105
	v_fmac_f32_e32 v150, v235, v152
	v_max_f32_e32 v153, 0, v113
	v_fmac_f32_e32 v151, v243, v153
	v_add_u32_e32 v145, 4, v145
	v_add_u32_e32 v146, 4, v146
	v_cndmask_b32_e64 v150, v225, v150, s[38:39]
	s_add_u32 s36, s36, 0xc000
	s_addc_u32 s37, s37, 0
	global_store_dword v144, v150, s[36:37]
	v_cndmask_b32_e64 v151, v225, v151, s[40:41]
	s_add_u32 s36, s36, 0x4000
	s_addc_u32 s37, s37, 0
	global_store_dword v144, v151, s[36:37]
	v_add_u32_e32 v148, 0x80, v148
	ds_read_b128 v[228:231], v148 offset:0
	ds_read_b128 v[232:235], v148 offset:16
	ds_read_b128 v[236:239], v148 offset:32
	ds_read_b128 v[240:243], v148 offset:48
	v_add_u32_e32 v147, 0x1200, v147
	ds_read_b128 v[66:69], v147 offset:0
	ds_read_b128 v[70:73], v147 offset:32
	ds_read_b128 v[74:77], v147 offset:64
	ds_read_b128 v[78:81], v147 offset:96
	s_waitcnt lgkmcnt(8)
	v_mfma_f32_32x32x16_f16 v[98:113], v[82:85], v[18:21], 0
	v_mfma_f32_32x32x16_f16 v[98:113], v[86:89], v[22:25], v[98:113]
	v_mfma_f32_32x32x16_f16 v[98:113], v[90:93], v[26:29], v[98:113]
	v_mfma_f32_32x32x16_f16 v[98:113], v[94:97], v[30:33], v[98:113]
	v_cmp_le_i32_e64 s[38:39], v55, v145
	v_cmp_le_i32_e64 s[40:41], v55, v146
	v_max_f32_e32 v152, 0, v2
	v_fma_f32 v150, v114, v152, 0
	v_max_f32_e32 v153, 0, v10
	v_fma_f32 v151, v122, v153, 0
	v_max_f32_e32 v152, 0, v6
	v_fmac_f32_e32 v150, v118, v152
	v_max_f32_e32 v153, 0, v14
	v_fmac_f32_e32 v151, v126, v153
	v_max_f32_e32 v152, 0, v3
	v_fmac_f32_e32 v150, v115, v152
	v_max_f32_e32 v153, 0, v11
	v_fmac_f32_e32 v151, v123, v153
	v_max_f32_e32 v152, 0, v7
	v_fmac_f32_e32 v150, v119, v152
	v_max_f32_e32 v153, 0, v15
	v_fmac_f32_e32 v151, v127, v153
	v_max_f32_e32 v152, 0, v4
	v_fmac_f32_e32 v150, v116, v152
	v_max_f32_e32 v153, 0, v12
	v_fmac_f32_e32 v151, v124, v153
	v_max_f32_e32 v152, 0, v8
	v_fmac_f32_e32 v150, v120, v152
	v_max_f32_e32 v153, 0, v16
	v_fmac_f32_e32 v151, v128, v153
	v_max_f32_e32 v152, 0, v5
	v_fmac_f32_e32 v150, v117, v152
	v_max_f32_e32 v153, 0, v13
	v_fmac_f32_e32 v151, v125, v153
	v_max_f32_e32 v152, 0, v9
	v_fmac_f32_e32 v150, v121, v152
	v_max_f32_e32 v153, 0, v17
	v_fmac_f32_e32 v151, v129, v153
	v_add_u32_e32 v145, 4, v145
	v_add_u32_e32 v146, 4, v146
	v_cndmask_b32_e64 v150, v225, v150, s[38:39]
	s_add_u32 s36, s36, 0xc000
	s_addc_u32 s37, s37, 0
	global_store_dword v144, v150, s[36:37]
	v_cndmask_b32_e64 v151, v225, v151, s[40:41]
	s_add_u32 s36, s36, 0x4000
	s_addc_u32 s37, s37, 0
	global_store_dword v144, v151, s[36:37]
	v_add_u32_e32 v148, 0x80, v148
	ds_read_b128 v[114:117], v148 offset:0
	ds_read_b128 v[118:121], v148 offset:16
	ds_read_b128 v[122:125], v148 offset:32
	ds_read_b128 v[126:129], v148 offset:48
	v_add_u32_e32 v147, 0x1200, v147
	ds_read_b128 v[82:85], v147 offset:0
	ds_read_b128 v[86:89], v147 offset:32
	ds_read_b128 v[90:93], v147 offset:64
	ds_read_b128 v[94:97], v147 offset:96
	s_waitcnt lgkmcnt(8)
; #define LAS __attribute__((address_space(3)))
; __device__ __forceinline__ f32x16 mma32(const h16x8 a, const h16x8 b, const f32x16 c) { return __builtin_amdgcn_mfma_f32_32x32x16_f16(a, b, c, 0, 0, 0); }
; __device__ __forceinline__ void dsa_select_item(CParams& p, LAS unsigned char* lds, int b, int qblk, int tid_in, int wave) {
;     ...
;             for (int a = 0; a < 8; ++a) {
;                 f32x16 acc;
; #pragma unroll
;                 for (int i = 0; i < 16; ++i) acc[i] = 0.f;
; #pragma unroll
;                 for (int s = 0; s < 4; ++s) acc = mma32(*(const LAS h16x8*)(Aq + (32 * a + r) * 72 + 16 * s + 8 * hk), bf[s], acc);
; #pragma unroll
;                 for (int qq = 0; qq < 2; ++qq) { const int qi = 4 * a + 2 * hk + qq;
;                     const f32x4 w0 = *(const LAS f32x4*)(Wq + qi * 8), w1 = *(const LAS f32x4*)(Wq + qi * 8 + 4);
;                     float sv = 0.f;
; #pragma unroll
;                     for (int e = 0; e < 4; ++e) { sv += w0[e] * fmaxf(acc[8 * qq + e], 0.f); sv += w1[e] * fmaxf(acc[8 * qq + 4 + e], 0.f); }
;                     const int qpq = qblk * 32 + qi;
;                     scw[(size_t)qi * 4096 + kp] = kp <= qpq ? sv : -INFINITY; }
;             }
; #pragma unroll
;             for (int s = 0; s < 4; ++s) bf[s] = bn[s];
	v_mfma_f32_32x32x16_f16 v[2:17], v[66:69], v[18:21], 0
	v_mfma_f32_32x32x16_f16 v[2:17], v[70:73], v[22:25], v[2:17]
	v_mfma_f32_32x32x16_f16 v[2:17], v[74:77], v[26:29], v[2:17]
	v_mfma_f32_32x32x16_f16 v[2:17], v[78:81], v[30:33], v[2:17]
	v_cmp_le_i32_e64 s[38:39], v55, v145
	v_cmp_le_i32_e64 s[40:41], v55, v146
	v_max_f32_e32 v152, 0, v98
	v_fma_f32 v150, v228, v152, 0
	v_max_f32_e32 v153, 0, v106
	v_fma_f32 v151, v236, v153, 0
	v_max_f32_e32 v152, 0, v102
	v_fmac_f32_e32 v150, v232, v152
	v_max_f32_e32 v153, 0, v110
	v_fmac_f32_e32 v151, v240, v153
	v_max_f32_e32 v152, 0, v99
	v_fmac_f32_e32 v150, v229, v152
	v_max_f32_e32 v153, 0, v107
	v_fmac_f32_e32 v151, v237, v153
	v_max_f32_e32 v152, 0, v103
	v_fmac_f32_e32 v150, v233, v152
	v_max_f32_e32 v153, 0, v111
	v_fmac_f32_e32 v151, v241, v153
	v_max_f32_e32 v152, 0, v100
	v_fmac_f32_e32 v150, v230, v152
	v_max_f32_e32 v153, 0, v108
	v_fmac_f32_e32 v151, v238, v153
	v_max_f32_e32 v152, 0, v104
	v_fmac_f32_e32 v150, v234, v152
	v_max_f32_e32 v153, 0, v112
	v_fmac_f32_e32 v151, v242, v153
	v_max_f32_e32 v152, 0, v101
	v_fmac_f32_e32 v150, v231, v152
	v_max_f32_e32 v153, 0, v109
	v_fmac_f32_e32 v151, v239, v153
	v_max_f32_e32 v152, 0, v105
	v_fmac_f32_e32 v150, v235, v152
	v_max_f32_e32 v153, 0, v113
	v_fmac_f32_e32 v151, v243, v153
	v_add_u32_e32 v145, 4, v145
	v_add_u32_e32 v146, 4, v146
	v_cndmask_b32_e64 v150, v225, v150, s[38:39]
	s_add_u32 s36, s36, 0xc000
	s_addc_u32 s37, s37, 0
	global_store_dword v144, v150, s[36:37]
	v_cndmask_b32_e64 v151, v225, v151, s[40:41]
	s_add_u32 s36, s36, 0x4000
	s_addc_u32 s37, s37, 0
	global_store_dword v144, v151, s[36:37]
	v_add_u32_e32 v148, 0x80, v148
	ds_read_b128 v[228:231], v148 offset:0
	ds_read_b128 v[232:235], v148 offset:16
	ds_read_b128 v[236:239], v148 offset:32
	ds_read_b128 v[240:243], v148 offset:48
	s_waitcnt lgkmcnt(4)
	v_mfma_f32_32x32x16_f16 v[98:113], v[82:85], v[18:21], 0
	v_mfma_f32_32x32x16_f16 v[98:113], v[86:89], v[22:25], v[98:113]
	v_mfma_f32_32x32x16_f16 v[98:113], v[90:93], v[26:29], v[98:113]
	v_mfma_f32_32x32x16_f16 v[98:113], v[94:97], v[30:33], v[98:113]
	v_cmp_le_i32_e64 s[38:39], v55, v145
	v_cmp_le_i32_e64 s[40:41], v55, v146
	v_max_f32_e32 v152, 0, v2
	v_fma_f32 v150, v114, v152, 0
	v_max_f32_e32 v153, 0, v10
	v_fma_f32 v151, v122, v153, 0
	v_max_f32_e32 v152, 0, v6
	v_fmac_f32_e32 v150, v118, v152
	v_max_f32_e32 v153, 0, v14
	v_fmac_f32_e32 v151, v126, v153
	v_max_f32_e32 v152, 0, v3
	v_fmac_f32_e32 v150, v115, v152
	v_max_f32_e32 v153, 0, v11
	v_fmac_f32_e32 v151, v123, v153
	v_max_f32_e32 v152, 0, v7
	v_fmac_f32_e32 v150, v119, v152
	v_max_f32_e32 v153, 0, v15
	v_fmac_f32_e32 v151, v127, v153
	v_max_f32_e32 v152, 0, v4
	v_fmac_f32_e32 v150, v116, v152
	v_max_f32_e32 v153, 0, v12
	v_fmac_f32_e32 v151, v124, v153
	v_max_f32_e32 v152, 0, v8
	v_fmac_f32_e32 v150, v120, v152
	v_max_f32_e32 v153, 0, v16
	v_fmac_f32_e32 v151, v128, v153
	v_max_f32_e32 v152, 0, v5
	v_fmac_f32_e32 v150, v117, v152
	v_max_f32_e32 v153, 0, v13
	v_fmac_f32_e32 v151, v125, v153
	v_max_f32_e32 v152, 0, v9
	v_fmac_f32_e32 v150, v121, v152
	v_max_f32_e32 v153, 0, v17
	v_fmac_f32_e32 v151, v129, v153
	v_add_u32_e32 v145, 4, v145
	v_add_u32_e32 v146, 4, v146
	v_cndmask_b32_e64 v150, v225, v150, s[38:39]
	s_add_u32 s36, s36, 0xc000
	s_addc_u32 s37, s37, 0
	global_store_dword v144, v150, s[36:37]
	v_cndmask_b32_e64 v151, v225, v151, s[40:41]
	s_add_u32 s36, s36, 0x4000
	s_addc_u32 s37, s37, 0
	global_store_dword v144, v151, s[36:37]
	v_cmp_le_i32_e64 s[38:39], v55, v145
	v_cmp_le_i32_e64 s[40:41], v55, v146
	s_waitcnt lgkmcnt(0)
	v_max_f32_e32 v152, 0, v98
	v_fma_f32 v150, v228, v152, 0
	v_max_f32_e32 v153, 0, v106
	v_fma_f32 v151, v236, v153, 0
	v_max_f32_e32 v152, 0, v102
	v_fmac_f32_e32 v150, v232, v152
	v_max_f32_e32 v153, 0, v110
	v_fmac_f32_e32 v151, v240, v153
	v_max_f32_e32 v152, 0, v99
	v_fmac_f32_e32 v150, v229, v152
	v_max_f32_e32 v153, 0, v107
	v_fmac_f32_e32 v151, v237, v153
	v_max_f32_e32 v152, 0, v103
	v_fmac_f32_e32 v150, v233, v152
	v_max_f32_e32 v153, 0, v111
	v_fmac_f32_e32 v151, v241, v153
	v_max_f32_e32 v152, 0, v100
	v_fmac_f32_e32 v150, v230, v152
	v_max_f32_e32 v153, 0, v108
	v_fmac_f32_e32 v151, v238, v153
	v_max_f32_e32 v152, 0, v104
	v_fmac_f32_e32 v150, v234, v152
	v_max_f32_e32 v153, 0, v112
	v_fmac_f32_e32 v151, v242, v153
	v_max_f32_e32 v152, 0, v101
	v_fmac_f32_e32 v150, v231, v152
	v_max_f32_e32 v153, 0, v109
	v_fmac_f32_e32 v151, v239, v153
	v_max_f32_e32 v152, 0, v105
	v_fmac_f32_e32 v150, v235, v152
	v_max_f32_e32 v153, 0, v113
	v_fmac_f32_e32 v151, v243, v153
	v_add_u32_e32 v145, 4, v145
	v_add_u32_e32 v146, 4, v146
	v_cndmask_b32_e64 v150, v225, v150, s[38:39]
	s_add_u32 s36, s36, 0xc000
	s_addc_u32 s37, s37, 0
	global_store_dword v144, v150, s[36:37]
	v_cndmask_b32_e64 v151, v225, v151, s[40:41]
	s_add_u32 s36, s36, 0x4000
	s_addc_u32 s37, s37, 0
	global_store_dword v144, v151, s[36:37]
	s_waitcnt vmcnt(16)
	v_mov_b64_e32 v[18:19], v[34:35]
	v_mov_b64_e32 v[22:23], v[38:39]
	v_mov_b64_e32 v[26:27], v[42:43]
	v_mov_b64_e32 v[30:31], v[46:47]
	v_add_u32_e32 v54, 0x100, v54
	v_mov_b64_e32 v[20:21], v[36:37]
	v_mov_b64_e32 v[24:25], v[40:41]
	v_mov_b64_e32 v[28:29], v[44:45]
	v_mov_b64_e32 v[32:33], v[48:49]
	s_andn2_b64 exec, exec, s[12:13]
	s_cbranch_execnz .LBB0_404

; __device__ __forceinline__ void dsa_select_item(CParams& p, LAS unsigned char* lds, int b, int qblk, int tid_in, int wave) {
;     ...
;         __syncthreads();
;         const int r = lane & 31, hk = lane >> 5;
;         const int nk32 = qblk + 1;
;         const h16* kp0 = proj + (size_t)(tb0 + r) * OD_N + 2816 + 8 * hk;
;         h16x8 bf[4], bn[4];
;         if (wave < nk32) {
; #pragma unroll
;             for (int s = 0; s < 4; ++s) bf[s] = *(const h16x8*)(kp0 + (size_t)wave * 32 * OD_N + 16 * s);
;         }
;         for (int kt = wave; kt < nk32; kt += 8) {
;             const int ktn = kt + 8 < nk32 ? kt + 8 : kt;
; #pragma unroll
;             for (int s = 0; s < 4; ++s) bn[s] = *(const h16x8*)(kp0 + (size_t)ktn * 32 * OD_N + 16 * s);
;             const int kp = kt * 32 + r;
.LBB0_453:
	s_or_b64 exec, exec, s[4:5]
	v_and_b32_e32 v58, 63, v2
	v_cmp_ge_i32_e32 vcc, s31, v182
	s_waitcnt lgkmcnt(0)
	s_barrier
	s_and_saveexec_b64 s[4:5], vcc
	s_movk_i32 s86, 0x1a00
	s_cbranch_execz .LBB0_458
	v_and_b32_e32 v59, 31, v2
	v_or_b32_e32 v0, s58, v59
	v_lshrrev_b32_e32 v6, 5, v58
	v_mul_u32_u24_e32 v0, 0x1800, v0
	v_lshl_add_u64 v[4:5], s[14:15], 0, v[0:1]
	v_lshlrev_b32_e32 v0, 4, v6
	v_lshl_add_u64 v[4:5], v[4:5], 0, v[0:1]
	s_mov_b64 s[6:7], 0x1600
	v_lshl_add_u64 v[50:51], v[4:5], 0, s[6:7]
	v_lshl_add_u64 v[4:5], v[50:51], 0, v[134:135]
	global_load_dwordx4 v[18:21], v[4:5], off
	global_load_dwordx4 v[22:25], v[4:5], off offset:32
	global_load_dwordx4 v[26:29], v[4:5], off offset:64
	global_load_dwordx4 v[30:33], v[4:5], off offset:96
	v_lshlrev_b32_e32 v2, 10, v2
	v_and_b32_e32 v2, 0x8000, v2
	v_mov_b32_e32 v3, v1
	v_lshlrev_b32_e32 v4, 1, v6
	v_lshl_add_u64 v[52:53], s[28:29], 0, v[2:3]
	v_mul_u32_u24_e32 v2, 0x90, v59
	s_add_i32 s6, 0, 0xa000
	v_add_u32_e32 v54, v190, v59
	v_add3_u32 v60, s84, 33, v4
	v_lshl_add_u32 v61, v6, 6, 0
	v_add3_u32 v0, v2, v0, s6
	s_mov_b64 s[12:13], 0
	v_mov_b32_e32 v62, v182
	s_waitcnt vmcnt(0)

; #define LAS __attribute__((address_space(3)))
; __device__ __forceinline__ void phase_gdn_scan(const int wid_s, CParams& p, LAS unsigned char* lds) {
;     int tid_ = TIDX; asm volatile("" : "+v"(tid_));
;     const int tid = tid_, lane = tid & 63, wave = tid >> 6, lr = lane & 15, lq = lane >> 4;
;     unsigned char* ws = p.ws; unsigned char* R = ws + WS_R;
;     const h16* proj = (const h16*)(R + R_PROJ); h16* y = (h16*)(R + R_Y);
;     const h16* qg = (const h16*)(R + R_QG); const h16* kdt = (const h16*)(R + R_KDT); const h16* intra = (const h16*)(R + R_INTRA);
;     const float* gcl = (const float*)(ws + WS_GCL);
;     LAS h16* St = (LAS h16*)lds;
;     LAS h16* Vnt = (LAS h16*)(lds + 17408);
;     for (int chain = blockIdx.x; chain < 256; chain += gridDim.x) {
;         const int b = chain >> 4, h = (chain >> 2) & 3, sl = chain & 3;
;         for (int i = tid; i < 32 * 136; i += NTHREADS) St[i] = (h16)0.f;
;         f32x4 st[2] = {{0.f, 0.f, 0.f, 0.f}, {0.f, 0.f, 0.f, 0.f}};
;         const int vt = wave & 1, wq = wave >> 1;
;         __syncthreads();
;         int cur = 0;
;         h16x8 wf[4], qf[4], inf[2], kf[2][2]; h16x4 uu; float egl;
;         h16x8 wfn[4], qfn[4], infn[2], kfn[2][2]; h16x4 uun; float egln;
.LBB0_1278:
	s_andn2_b64 vcc, exec, s[4:5]
	s_cbranch_vccnz .LBB0_1319
	v_readlane_b32 s6, v253, 10
	v_readlane_b32 s4, v253, 1
	v_readlane_b32 s7, v253, 11
	v_readlane_b32 s5, v253, 2
	s_waitcnt vmcnt(0)
	v_mov_b32_e32 v2, v219
	s_andn2_b64 vcc, exec, s[6:7]
	s_cbranch_vccnz .LBB0_1287
	s_load_dwordx2 s[6:7], s[4:5], 0xc8
	s_waitcnt vmcnt(0)
	v_and_b32_e32 v114, 15, v2
	s_waitcnt lgkmcnt(0)
	v_bfe_u32 v3, v2, 4, 2
	v_ashrrev_i32_e32 v7, 7, v2
	v_lshlrev_b32_e32 v0, 1, v114
	s_add_u32 s4, s6, 0xfd86180
	s_addc_u32 s5, s7, 0
	s_add_u32 s8, s6, 0x31d86180
	s_addc_u32 s9, s7, 0
	s_add_u32 s15, s6, 0xe781180
	v_lshlrev_b32_e32 v9, 4, v7
	v_lshlrev_b32_e32 v118, 4, v3
	v_mov_b32_e32 v119, v1
	s_addc_u32 s16, s7, 0
	s_movk_i32 s10, 0x1100
	v_or_b32_e32 v116, v9, v114
	v_lshrrev_b32_e32 v6, 2, v2
	v_ashrrev_i32_e32 v117, 31, v9
	v_lshl_add_u64 v[10:11], s[6:7], 0, v[118:119]
	v_lshl_add_u64 v[12:13], s[6:7], 0, v[0:1]
	s_mov_b64 s[6:7], 0x29d86580
	v_cmp_gt_i32_e32 vcc, s10, v2
	v_and_b32_e32 v6, 16, v6
	v_lshlrev_b32_e32 v8, 2, v3
	s_mov_b64 s[10:11], 0x35d86180
	v_lshl_add_u64 v[128:129], v[12:13], 0, s[6:7]
	v_lshlrev_b64 v[12:13], 7, v[116:117]
	v_add_u32_e32 v5, 0, v0
	v_lshlrev_b32_e32 v4, 3, v3
	v_lshlrev_b32_e32 v120, 5, v7
	v_lshl_add_u64 v[122:123], v[10:11], 0, s[10:11]
	v_or_b32_e32 v3, v6, v114
	v_or_b32_e32 v14, v8, v6
	v_lshl_add_u64 v[10:11], v[10:11], 0, v[12:13]
	s_mov_b64 s[6:7], 0x39d86180
	v_add_u32_e32 v15, v5, v120
	v_mad_u32_u24 v115, v3, s60, 0
	v_lshl_add_u64 v[130:131], v[10:11], 0, s[6:7]
	v_or_b32_e32 v132, 16, v120
	v_lshlrev_b32_e32 v0, 7, v3
	v_mul_u32_u24_e32 v3, 0x90, v14
	v_readlane_b32 s6, v253, 54
	v_lshl_add_u64 v[124:125], s[4:5], 0, v[118:119]
	v_lshl_add_u64 v[126:127], s[8:9], 0, v[118:119]
	v_or_b32_e32 v119, v8, v9
	v_lshl_add_u32 v148, v7, 6, v5
	v_ashrrev_i32_e32 v121, 31, v120
	v_ashrrev_i32_e32 v133, 31, v132
	v_add3_u32 v117, v115, v0, v118
	v_mul_u32_u24_e32 v149, 0x110, v14
	v_add_u32_e32 v150, 0xfffffe00, v2
	v_lshl_add_u32 v151, v2, 1, 0
	v_add_u32_e32 v152, 64, v116
	v_lshlrev_b32_e32 v0, 1, v4
	v_lshlrev_b32_e32 v134, 1, v6
	v_lshlrev_b32_e32 v136, 1, v8
	v_add_u32_e32 v153, v15, v3
	v_readlane_b32 s17, v253, 56
	s_mov_b32 s18, s6
	v_readlane_b32 s7, v253, 55
	v_readlane_b32 s98, v253, 0
	s_cmp_lg_u32 s98, 0x100
	s_cbranch_scc1 .Lscan_noremap
	s_and_b32 s98, s18, 7
	s_lshl_b32 s98, s98, 5
	s_lshr_b32 s99, s18, 3
	s_or_b32 s18, s98, s99
	s_lshl_b32 s17, s18, 8
.Lscan_noremap:
.LBB0_1281:
	s_and_saveexec_b64 s[10:11], vcc
	s_cbranch_execz .LBB0_1284
	s_mov_b64 s[12:13], 0
	v_mov_b32_e32 v2, v151
	v_mov_b32_e32 v3, v150
